# gdn scan consumer: 32 packed state-decay multiplies beside the MFMAs split into scalar pairs (bit-identical), 3 fillers per MFMA gap
# baseline (speedup 1.0000x reference)
; __device__ __forceinline__ float bf2f(bf16_t b) { return asf((unsigned)b << 16); }
; __device__ __forceinline__ int crow(int r, int hi) { return (r & 3) + 8 * (r >> 2) + 4 * hi; }
; __device__ __forceinline__ bf16x8 ldA_perm(const LAS bf16_t* p) { s16x4 a = *(const LAS s16x4*)p; s16x4 b = *(const LAS s16x4*)(p + 8); return (bf16x8){a[0], a[1], a[2], a[3], b[0], b[1], b[2], b[3]}; }
; #define LDS_BARRIER() do { asm volatile("s_waitcnt lgkmcnt(0)" ::: "memory"); __builtin_amdgcn_s_barrier(); asm volatile("" ::: "memory"); } while (0)
; #define GDN_LDF_WQ(F, td_) do { _Pragma("unroll") for (int tc = 0; tc < 2; ++tc) _Pragma("unroll") for (int s_ = 0; s_ < 2; ++s_) { const int ko_ = 32 * (td_) + 16 * s_ + 4 * hh; \
;                     F[tc * 2 + s_] = ldA_perm(WNs + (32 * tc + l31) * 136 + ko_); F[4 + tc * 2 + s_] = ldA_perm(QD + (32 * tc + l31) * 136 + ko_); } } while (0)
; __device__ __forceinline__ void gdn_scan(const Ctx& c, const Params& p, int e) {
;     ...
;             for (int n = 0; n < 128; ++n) {
;                 LDS_BARRIER();
;                 if (c.wave < 2) {
;                 const float gt = gtn; if (n + 1 < 128) gtn = GC[(size_t)bh * 128 + n + 1];
;                 f32x16 av[2];
; #pragma unroll
;                 for (int tc = 0; tc < 2; ++tc)
; #pragma unroll
;                     for (int r = 0; r < 16; ++r) av[tc][r] = bf2f(UT[(32 * tc + crow(r, hh)) * 136 + e0 + l31]);
;                 f32x16 ao[2] = {(f32x16){}, (f32x16){}};
;                 bf16x8 fa[8], fb[8];
;     ...
;                 GDN_LDF_WQ(fa, 0);
;                 GDN_LDF_WQ(fb, 1); GDN_MMA_WQ(fa, 0);
;                 GDN_LDF_WQ(fa, 2); GDN_MMA_WQ(fb, 1);
;                 GDN_LDF_WQ(fb, 3); GDN_MMA_WQ(fa, 2);
; #pragma unroll
;                 for (int tc = 0; tc < 2; ++tc)
; #pragma unroll
;                     for (int ts = 0; ts < 2; ++ts)
; #pragma unroll
;                         for (int s_ = 0; s_ < 2; ++s_) fa[tc * 4 + ts * 2 + s_] = ldA_perm(QK + (32 * tc + l31) * 72 + 32 * ts + 16 * s_ + 4 * hh);
;                 GDN_MMA_WQ(fb, 3);
;     ...
;                 bf16x8 Vb[2][2];
; #pragma unroll
;                 for (int tc = 0; tc < 2; ++tc) { Vb[tc][0] = pkfrag(av[tc], 0); Vb[tc][1] = pkfrag(av[tc], 1); }
.LBB0_525:
	s_waitcnt lgkmcnt(0)
	s_barrier
	v_cndmask_b32_e64 v1, 0, 1, s[12:13]
	v_cmp_ne_u32_e64 s[4:5], 1, v1
	s_andn2_b64 vcc, exec, s[12:13]
	s_cbranch_vccnz .LBB0_524
	v_mov_b64_e32 v[252:253], s[2:3]
	v_add_u32_e32 v174, 0x4000, v186
	v_add_u32_e32 v175, 0x4000, v187
	global_load_dword v253, v[252:253], off
	v_add_u32_e32 v1, v168, v188
	ds_read2_b64 v[232:235], v14 offset0:0 offset1:2
	ds_read2_b64 v[236:239], v15 offset0:0 offset1:2
	ds_read2_b64 v[240:243], v14 offset0:4 offset1:6
	ds_read2_b64 v[244:247], v15 offset0:4 offset1:6
	ds_read2_b64 v[248:251], v174 offset0:128 offset1:130
	ds_read2_b64 v[2:5], v186 offset0:0 offset1:2
	v_add_u32_e32 v252, 0x1000, v1
	s_bitcmp1_b32 s21, 0
	s_cselect_b32 s35, 0x2400, 0
	v_cvt_pk_bf16_f32 v200, v64, v65
	v_cvt_pk_bf16_f32 v201, v66, v67
	v_cvt_pk_bf16_f32 v202, v68, v69
	v_cvt_pk_bf16_f32 v203, v70, v71
	v_cvt_pk_bf16_f32 v204, v72, v73
	v_cvt_pk_bf16_f32 v205, v74, v75
	v_cvt_pk_bf16_f32 v206, v76, v77
	v_cvt_pk_bf16_f32 v207, v78, v79
	s_waitcnt lgkmcnt(5)
	v_mfma_f32_32x32x16_bf16 v[80:95], v[232:235], v[6:9], 0
	ds_read2_b64 v[232:235], v175 offset0:128 offset1:130
	s_waitcnt lgkmcnt(5)
	v_mfma_f32_32x32x16_bf16 v[112:127], v[236:239], v[6:9], 0
	ds_read2_b64 v[236:239], v187 offset0:0 offset1:2
	s_waitcnt lgkmcnt(5)
	v_mfma_f32_32x32x16_bf16 v[80:95], v[240:243], v[10:13], v[80:95]
	ds_read2_b64 v[240:243], v174 offset0:132 offset1:134
	s_waitcnt lgkmcnt(5)
	v_mfma_f32_32x32x16_bf16 v[112:127], v[244:247], v[10:13], v[112:127]
	ds_read2_b64 v[244:247], v186 offset0:4 offset1:6
	s_waitcnt lgkmcnt(5)
	v_mfma_f32_32x32x16_bf16 v[80:95], v[248:251], v[200:203], v[80:95]
	ds_read2_b64 v[248:251], v175 offset0:132 offset1:134
	v_cvt_pk_bf16_f32 v208, v48, v49
	v_cvt_pk_bf16_f32 v209, v50, v51
	v_cvt_pk_bf16_f32 v210, v52, v53
	s_waitcnt lgkmcnt(5)
	v_mfma_f32_32x32x16_bf16 v[96:111], v[2:5], v[200:203], 0
	ds_read2_b64 v[2:5], v187 offset0:4 offset1:6
	v_cvt_pk_bf16_f32 v211, v54, v55
	v_cvt_pk_bf16_f32 v212, v56, v57
	v_cvt_pk_bf16_f32 v213, v58, v59
	s_waitcnt lgkmcnt(5)
	v_mfma_f32_32x32x16_bf16 v[112:127], v[232:235], v[200:203], v[112:127]
	ds_read2_b64 v[232:235], v174 offset0:136 offset1:138
	v_cvt_pk_bf16_f32 v214, v60, v61
	v_cvt_pk_bf16_f32 v215, v62, v63
	v_cvt_pk_bf16_f32 v216, v32, v33
	s_waitcnt lgkmcnt(5)
	v_mfma_f32_32x32x16_bf16 v[128:143], v[236:239], v[200:203], 0
	ds_read2_b64 v[236:239], v186 offset0:8 offset1:10
	v_cvt_pk_bf16_f32 v217, v34, v35
	v_cvt_pk_bf16_f32 v218, v36, v37
	v_cvt_pk_bf16_f32 v219, v38, v39
	s_waitcnt lgkmcnt(5)
	v_mfma_f32_32x32x16_bf16 v[80:95], v[240:243], v[204:207], v[80:95]
	ds_read2_b64 v[240:243], v175 offset0:136 offset1:138
	v_cvt_pk_bf16_f32 v220, v40, v41
	v_cvt_pk_bf16_f32 v221, v42, v43
	v_cvt_pk_bf16_f32 v222, v44, v45
	s_waitcnt lgkmcnt(5)
	v_mfma_f32_32x32x16_bf16 v[96:111], v[244:247], v[204:207], v[96:111]
	ds_read2_b64 v[244:247], v187 offset0:8 offset1:10
	v_cvt_pk_bf16_f32 v223, v46, v47
	v_cvt_pk_bf16_f32 v224, v16, v17
	v_cvt_pk_bf16_f32 v225, v18, v19
	s_waitcnt lgkmcnt(5)
	v_mfma_f32_32x32x16_bf16 v[112:127], v[248:251], v[204:207], v[112:127]
	ds_read2_b64 v[248:251], v174 offset0:140 offset1:142
	v_cvt_pk_bf16_f32 v226, v20, v21
	v_cvt_pk_bf16_f32 v227, v22, v23
	v_cvt_pk_bf16_f32 v228, v24, v25
	s_waitcnt lgkmcnt(5)
	v_mfma_f32_32x32x16_bf16 v[128:143], v[2:5], v[204:207], v[128:143]
	ds_read2_b64 v[2:5], v186 offset0:12 offset1:14
	v_cvt_pk_bf16_f32 v229, v26, v27
	v_cvt_pk_bf16_f32 v230, v28, v29
	v_cvt_pk_bf16_f32 v231, v30, v31
	s_waitcnt lgkmcnt(5)
	v_mfma_f32_32x32x16_bf16 v[80:95], v[232:235], v[208:211], v[80:95]
	ds_read2_b64 v[232:235], v175 offset0:140 offset1:142
	v_mul_f32_e32 v64, v150, v64
	v_mul_f32_e32 v65, v150, v65
	v_mul_f32_e32 v66, v150, v66
	s_waitcnt lgkmcnt(5)
	v_mfma_f32_32x32x16_bf16 v[96:111], v[236:239], v[208:211], v[96:111]
	ds_read2_b64 v[236:239], v187 offset0:12 offset1:14
	v_mul_f32_e32 v67, v150, v67
	v_mul_f32_e32 v68, v150, v68
	v_mul_f32_e32 v69, v150, v69
	s_waitcnt lgkmcnt(5)
	v_mfma_f32_32x32x16_bf16 v[112:127], v[240:243], v[208:211], v[112:127]
	ds_read2_b64 v[240:243], v174 offset0:144 offset1:146
	v_mul_f32_e32 v70, v150, v70
	v_mul_f32_e32 v71, v150, v71
	v_mul_f32_e32 v72, v150, v72
	s_waitcnt lgkmcnt(5)
	v_mfma_f32_32x32x16_bf16 v[128:143], v[244:247], v[208:211], v[128:143]
	ds_read2_b64 v[244:247], v186 offset0:16 offset1:18
	v_mul_f32_e32 v73, v150, v73
	v_mul_f32_e32 v74, v150, v74
	v_mul_f32_e32 v75, v150, v75
	s_waitcnt lgkmcnt(5)
	v_mfma_f32_32x32x16_bf16 v[80:95], v[248:251], v[212:215], v[80:95]
	ds_read2_b64 v[248:251], v175 offset0:144 offset1:146
	v_mul_f32_e32 v76, v150, v76
	v_mul_f32_e32 v77, v150, v77
	v_mul_f32_e32 v78, v150, v78
	s_waitcnt lgkmcnt(5)
	v_mfma_f32_32x32x16_bf16 v[96:111], v[2:5], v[212:215], v[96:111]
	ds_read2_b64 v[2:5], v187 offset0:16 offset1:18
	v_mul_f32_e32 v79, v150, v79
	v_mul_f32_e32 v48, v150, v48
	v_mul_f32_e32 v49, v150, v49
	s_waitcnt lgkmcnt(5)
	v_mfma_f32_32x32x16_bf16 v[112:127], v[232:235], v[212:215], v[112:127]
	ds_read2_b64 v[232:235], v174 offset0:148 offset1:150
	v_mul_f32_e32 v50, v150, v50
	v_mul_f32_e32 v51, v150, v51
	v_mul_f32_e32 v52, v150, v52
	s_waitcnt lgkmcnt(5)
	v_mfma_f32_32x32x16_bf16 v[128:143], v[236:239], v[212:215], v[128:143]
	ds_read2_b64 v[236:239], v186 offset0:20 offset1:22
	v_mul_f32_e32 v53, v150, v53
	v_mul_f32_e32 v54, v150, v54
	v_mul_f32_e32 v55, v150, v55
	s_waitcnt lgkmcnt(5)
	v_mfma_f32_32x32x16_bf16 v[80:95], v[240:243], v[216:219], v[80:95]
	ds_read2_b64 v[240:243], v175 offset0:148 offset1:150
	v_mul_f32_e32 v56, v150, v56
	v_mul_f32_e32 v57, v150, v57
	v_mul_f32_e32 v58, v150, v58
	s_waitcnt lgkmcnt(5)
; #define GDN_LDF_K(F, tdp_) do { _Pragma("unroll") for (int t2_ = 0; t2_ < 2; ++t2_) _Pragma("unroll") for (int tc = 0; tc < 2; ++tc) _Pragma("unroll") for (int s_ = 0; s_ < 2; ++s_) \
;                     F[t2_ * 4 + tc * 2 + s_] = ldA_perm(KDT + (32 * (2 * (tdp_) + t2_) + l31) * 72 + 32 * tc + 16 * s_ + 4 * hh); } while (0)
; __device__ __forceinline__ void gdn_scan(const Ctx& c, const Params& p, int e) {
;     ...
;                 bf16x8 Vb[2][2];
; #pragma unroll
;                 for (int tc = 0; tc < 2; ++tc) { Vb[tc][0] = pkfrag(av[tc], 0); Vb[tc][1] = pkfrag(av[tc], 1); }
;     ...
;                 GDN_LDF_K(fb, 0);
; #pragma unroll
;                 for (int ts = 0; ts < 2; ++ts)
; #pragma unroll
;                     for (int s_ = 0; s_ < 2; ++s_)
; #pragma unroll
;                         for (int tc = 0; tc < 2; ++tc) ao[tc] = __builtin_amdgcn_mfma_f32_32x32x16_bf16(fa[tc * 4 + ts * 2 + s_], Vb[ts][s_], ao[tc], 0, 0, 0);
;                 GDN_LDF_K(fa, 1); GDN_MMA_K(fb, 0);
;                 GDN_MMA_K(fa, 1);
	v_mfma_f32_32x32x16_bf16 v[96:111], v[244:247], v[216:219], v[96:111]
	ds_read2_b64 v[244:247], v187 offset0:20 offset1:22
	v_mul_f32_e32 v59, v150, v59
	v_mul_f32_e32 v60, v150, v60
	v_mul_f32_e32 v61, v150, v61
	s_waitcnt lgkmcnt(5)
	v_mfma_f32_32x32x16_bf16 v[112:127], v[248:251], v[216:219], v[112:127]
	ds_read2_b64 v[248:251], v174 offset0:152 offset1:154
	v_mul_f32_e32 v62, v150, v62
	v_mul_f32_e32 v63, v150, v63
	v_mul_f32_e32 v32, v150, v32
	s_waitcnt lgkmcnt(5)
	v_mfma_f32_32x32x16_bf16 v[128:143], v[2:5], v[216:219], v[128:143]
	ds_read2_b64 v[2:5], v175 offset0:152 offset1:154
	v_mul_f32_e32 v33, v150, v33
	v_mul_f32_e32 v34, v150, v34
	v_mul_f32_e32 v35, v150, v35
	s_waitcnt lgkmcnt(5)
	v_mfma_f32_32x32x16_bf16 v[80:95], v[232:235], v[220:223], v[80:95]
	ds_read2_b64 v[232:235], v174 offset0:156 offset1:158
	v_mul_f32_e32 v36, v150, v36
	v_mul_f32_e32 v37, v150, v37
	v_mul_f32_e32 v38, v150, v38
	s_waitcnt lgkmcnt(5)
	v_mfma_f32_32x32x16_bf16 v[96:111], v[236:239], v[220:223], v[96:111]
	ds_read2_b64 v[236:239], v175 offset0:156 offset1:158
	v_mul_f32_e32 v39, v150, v39
	v_mul_f32_e32 v40, v150, v40
	v_mul_f32_e32 v41, v150, v41
	s_waitcnt lgkmcnt(5)
	v_mfma_f32_32x32x16_bf16 v[112:127], v[240:243], v[220:223], v[112:127]
	ds_read2_b64 v[240:243], v186 offset0:24 offset1:26
	v_mul_f32_e32 v42, v150, v42
	v_mul_f32_e32 v43, v150, v43
	v_mul_f32_e32 v44, v150, v44
	s_waitcnt lgkmcnt(5)
	v_mfma_f32_32x32x16_bf16 v[128:143], v[244:247], v[220:223], v[128:143]
	ds_read2_b64 v[244:247], v187 offset0:24 offset1:26
	v_mul_f32_e32 v45, v150, v45
	v_mul_f32_e32 v46, v150, v46
	v_mul_f32_e32 v47, v150, v47
	s_waitcnt lgkmcnt(5)
	v_mfma_f32_32x32x16_bf16 v[80:95], v[248:251], v[224:227], v[80:95]
	ds_read2_b64 v[248:251], v186 offset0:28 offset1:30
	v_mul_f32_e32 v16, v150, v16
	v_mul_f32_e32 v17, v150, v17
	v_mul_f32_e32 v18, v150, v18
	s_waitcnt lgkmcnt(5)
	v_mfma_f32_32x32x16_bf16 v[112:127], v[2:5], v[224:227], v[112:127]
	ds_read2_b64 v[2:5], v187 offset0:28 offset1:30
	v_mul_f32_e32 v19, v150, v19
	v_mul_f32_e32 v20, v150, v20
	v_mul_f32_e32 v21, v150, v21
	s_waitcnt lgkmcnt(5)
	v_mfma_f32_32x32x16_bf16 v[80:95], v[232:235], v[228:231], v[80:95]
	ds_read2_b64 v[232:235], v1 offset0:0 offset1:2
	v_mul_f32_e32 v22, v150, v22
	v_mul_f32_e32 v23, v150, v23
	v_mul_f32_e32 v24, v150, v24
	s_waitcnt lgkmcnt(5)
	v_mfma_f32_32x32x16_bf16 v[112:127], v[236:239], v[228:231], v[112:127]
	ds_read2_b64 v[236:239], v252 offset0:64 offset1:66
	v_mul_f32_e32 v25, v150, v25
	v_mul_f32_e32 v26, v150, v26
	v_mul_f32_e32 v27, v150, v27
	s_waitcnt lgkmcnt(5)
	v_mfma_f32_32x32x16_bf16 v[96:111], v[240:243], v[224:227], v[96:111]
	ds_read2_b64 v[240:243], v1 offset0:4 offset1:6
	v_mul_f32_e32 v28, v150, v28
	v_mul_f32_e32 v29, v150, v29
	v_mul_f32_e32 v30, v150, v30
	s_waitcnt lgkmcnt(5)
	v_mfma_f32_32x32x16_bf16 v[128:143], v[244:247], v[224:227], v[128:143]
	ds_read2_b64 v[244:247], v252 offset0:68 offset1:70
	v_mul_f32_e32 v31, v150, v31
	s_waitcnt lgkmcnt(5)
	v_mfma_f32_32x32x16_bf16 v[96:111], v[248:251], v[228:231], v[96:111]
	ds_read2_b64 v[248:251], v1 offset0:8 offset1:10
	s_waitcnt lgkmcnt(5)
	v_mfma_f32_32x32x16_bf16 v[128:143], v[2:5], v[228:231], v[128:143]
	ds_read2_b64 v[2:5], v252 offset0:72 offset1:74
	s_waitcnt vmcnt(0)
	v_mov_b32_e32 v150, v253
	s_nop 3
	v_cvt_pk_bf16_f32 v80, v80, v81
	v_cvt_pk_bf16_f32 v81, v82, v83
	v_cvt_pk_bf16_f32 v82, v84, v85
	v_cvt_pk_bf16_f32 v83, v86, v87
	v_cvt_pk_bf16_f32 v84, v88, v89
	v_cvt_pk_bf16_f32 v85, v90, v91
	v_cvt_pk_bf16_f32 v86, v92, v93
	v_cvt_pk_bf16_f32 v87, v94, v95
	v_cvt_pk_bf16_f32 v112, v112, v113
	v_cvt_pk_bf16_f32 v113, v114, v115
	v_cvt_pk_bf16_f32 v114, v116, v117
	v_cvt_pk_bf16_f32 v115, v118, v119
	v_cvt_pk_bf16_f32 v116, v120, v121
	v_cvt_pk_bf16_f32 v117, v122, v123
	v_cvt_pk_bf16_f32 v118, v124, v125
	v_cvt_pk_bf16_f32 v119, v126, v127
	v_add_u32_e32 v174, v169, v188
	v_add_u32_e32 v174, 0xcc00, v174
	v_add_u32_e32 v175, 0x1200, v174
	v_add_u32_e32 v253, 0x1200, v175
	s_waitcnt lgkmcnt(5)
	v_mfma_f32_32x32x16_bf16 v[96:111], v[232:235], v[80:83], v[96:111]
	ds_read2_b64 v[232:235], v1 offset0:12 offset1:14
	s_waitcnt lgkmcnt(5)
	v_mfma_f32_32x32x16_bf16 v[128:143], v[236:239], v[80:83], v[128:143]
	ds_read2_b64 v[236:239], v252 offset0:76 offset1:78
	v_add_u32_e32 v252, 0x1200, v253
	s_waitcnt lgkmcnt(5)
	v_mfma_f32_32x32x16_bf16 v[96:111], v[240:243], v[84:87], v[96:111]
	ds_read2_b64 v[240:243], v174 offset0:0 offset1:2
	s_waitcnt lgkmcnt(5)
; #define LAS __attribute__((address_space(3)))
; __device__ __forceinline__ bf16_t f2bf(float f) { return (bf16_t)(pk2(f, 0.f) & 0xffffu); }
; __device__ __forceinline__ int crow(int r, int hi) { return (r & 3) + 8 * (r >> 2) + 4 * hi; }
; #define GDN_LDF_K(F, tdp_) do { _Pragma("unroll") for (int t2_ = 0; t2_ < 2; ++t2_) _Pragma("unroll") for (int tc = 0; tc < 2; ++tc) _Pragma("unroll") for (int s_ = 0; s_ < 2; ++s_) \
;                     F[t2_ * 4 + tc * 2 + s_] = ldA_perm(KDT + (32 * (2 * (tdp_) + t2_) + l31) * 72 + 32 * tc + 16 * s_ + 4 * hh); } while (0)
; __device__ __forceinline__ void gdn_scan(const Ctx& c, const Params& p, int e) {
;     ...
;                 GDN_LDF_K(fb, 0);
; #pragma unroll
;                 for (int ts = 0; ts < 2; ++ts)
; #pragma unroll
;                     for (int s_ = 0; s_ < 2; ++s_)
; #pragma unroll
;                         for (int tc = 0; tc < 2; ++tc) ao[tc] = __builtin_amdgcn_mfma_f32_32x32x16_bf16(fa[tc * 4 + ts * 2 + s_], Vb[ts][s_], ao[tc], 0, 0, 0);
;                 GDN_LDF_K(fa, 1); GDN_MMA_K(fb, 0);
;                 GDN_MMA_K(fa, 1);
;     ...
;                 LAS bf16_t* ob = OTb + (n & 1) * 4608;
; #pragma unroll
;                 for (int tc = 0; tc < 2; ++tc)
; #pragma unroll
;                     for (int r = 0; r < 16; ++r) ob[(32 * tc + crow(r, hh)) * 72 + 32 * (c.wave & 1) + l31] = f2bf(ao[tc][r]);
	v_mfma_f32_32x32x16_bf16 v[128:143], v[244:247], v[84:87], v[128:143]
	ds_read2_b64 v[244:247], v175 offset0:0 offset1:2
	s_waitcnt lgkmcnt(5)
	v_mfma_f32_32x32x16_bf16 v[96:111], v[248:251], v[112:115], v[96:111]
	ds_read2_b64 v[248:251], v253 offset0:0 offset1:2
	s_waitcnt lgkmcnt(5)
	v_mfma_f32_32x32x16_bf16 v[128:143], v[2:5], v[112:115], v[128:143]
	ds_read2_b64 v[2:5], v252 offset0:0 offset1:2
	s_waitcnt lgkmcnt(5)
	v_mfma_f32_32x32x16_bf16 v[96:111], v[232:235], v[116:119], v[96:111]
	ds_read2_b64 v[232:235], v174 offset0:4 offset1:6
	s_waitcnt lgkmcnt(5)
	v_mfma_f32_32x32x16_bf16 v[128:143], v[236:239], v[116:119], v[128:143]
	ds_read2_b64 v[236:239], v175 offset0:4 offset1:6
	v_add_u32_e32 v1, s35, v195
	v_add_u32_e32 v1, v1, v190
	s_waitcnt lgkmcnt(5)
	v_mfma_f32_32x32x16_bf16 v[64:79], v[240:243], v[80:83], v[64:79]
	ds_read2_b64 v[240:243], v253 offset0:4 offset1:6
	s_waitcnt lgkmcnt(5)
	v_mfma_f32_32x32x16_bf16 v[48:63], v[244:247], v[80:83], v[48:63]
	ds_read2_b64 v[244:247], v252 offset0:4 offset1:6
	s_waitcnt lgkmcnt(5)
	v_mfma_f32_32x32x16_bf16 v[32:47], v[248:251], v[80:83], v[32:47]
	ds_read2_b64 v[248:251], v174 offset0:8 offset1:10
	s_waitcnt lgkmcnt(5)
	v_mfma_f32_32x32x16_bf16 v[16:31], v[2:5], v[80:83], v[16:31]
	ds_read2_b64 v[2:5], v175 offset0:8 offset1:10
	v_cvt_pk_bf16_f32 v88, v96, v97
	ds_write_b16 v1, v88 offset:0
	ds_write_b16_d16_hi v1, v88 offset:144
	s_waitcnt lgkmcnt(7)
	v_mfma_f32_32x32x16_bf16 v[64:79], v[232:235], v[84:87], v[64:79]
	ds_read2_b64 v[232:235], v253 offset0:8 offset1:10
	v_cvt_pk_bf16_f32 v89, v98, v99
	ds_write_b16 v1, v89 offset:288
	ds_write_b16_d16_hi v1, v89 offset:432
	s_waitcnt lgkmcnt(9)
	v_mfma_f32_32x32x16_bf16 v[48:63], v[236:239], v[84:87], v[48:63]
	ds_read2_b64 v[236:239], v252 offset0:8 offset1:10
	v_cvt_pk_bf16_f32 v90, v100, v101
	ds_write_b16 v1, v90 offset:1152
	ds_write_b16_d16_hi v1, v90 offset:1296
	s_waitcnt lgkmcnt(11)
	v_mfma_f32_32x32x16_bf16 v[32:47], v[240:243], v[84:87], v[32:47]
	ds_read2_b64 v[240:243], v174 offset0:12 offset1:14
	v_cvt_pk_bf16_f32 v91, v102, v103
	ds_write_b16 v1, v91 offset:1440
	ds_write_b16_d16_hi v1, v91 offset:1584
	s_waitcnt lgkmcnt(13)
	v_mfma_f32_32x32x16_bf16 v[16:31], v[244:247], v[84:87], v[16:31]
	ds_read2_b64 v[244:247], v175 offset0:12 offset1:14
	v_cvt_pk_bf16_f32 v88, v104, v105
	ds_write_b16 v1, v88 offset:2304
	s_waitcnt lgkmcnt(7)
	ds_write_b16_d16_hi v1, v88 offset:2448
	v_mfma_f32_32x32x16_bf16 v[64:79], v[248:251], v[112:115], v[64:79]
	ds_read2_b64 v[248:251], v253 offset0:12 offset1:14
	v_cvt_pk_bf16_f32 v89, v106, v107
	ds_write_b16 v1, v89 offset:2592
	ds_write_b16_d16_hi v1, v89 offset:2736
	v_mfma_f32_32x32x16_bf16 v[48:63], v[2:5], v[112:115], v[48:63]
	ds_read2_b64 v[2:5], v252 offset0:12 offset1:14
	v_cvt_pk_bf16_f32 v90, v108, v109
	ds_write_b16 v1, v90 offset:3456
	ds_write_b16_d16_hi v1, v90 offset:3600
	v_mfma_f32_32x32x16_bf16 v[32:47], v[232:235], v[112:115], v[32:47]
	v_cvt_pk_bf16_f32 v91, v110, v111
	ds_write_b16 v1, v91 offset:3744
	s_waitcnt lgkmcnt(7)
	ds_write_b16_d16_hi v1, v91 offset:3888
	v_cvt_pk_bf16_f32 v88, v128, v129
	ds_write_b16 v1, v88 offset:4608
	ds_write_b16_d16_hi v1, v88 offset:4752
	v_mfma_f32_32x32x16_bf16 v[16:31], v[236:239], v[112:115], v[16:31]
	v_cvt_pk_bf16_f32 v89, v130, v131
	ds_write_b16 v1, v89 offset:4896
	ds_write_b16_d16_hi v1, v89 offset:5040
	v_cvt_pk_bf16_f32 v90, v132, v133
	ds_write_b16 v1, v90 offset:5760
	ds_write_b16_d16_hi v1, v90 offset:5904
	v_mfma_f32_32x32x16_bf16 v[64:79], v[240:243], v[116:119], v[64:79]
	v_cvt_pk_bf16_f32 v91, v134, v135
	ds_write_b16 v1, v91 offset:6048
	s_waitcnt lgkmcnt(7)
	ds_write_b16_d16_hi v1, v91 offset:6192
	v_cvt_pk_bf16_f32 v88, v136, v137
	ds_write_b16 v1, v88 offset:6912
	ds_write_b16_d16_hi v1, v88 offset:7056
	v_mfma_f32_32x32x16_bf16 v[48:63], v[244:247], v[116:119], v[48:63]
	v_cvt_pk_bf16_f32 v89, v138, v139
	ds_write_b16 v1, v89 offset:7200
	ds_write_b16_d16_hi v1, v89 offset:7344
	v_cvt_pk_bf16_f32 v90, v140, v141
	ds_write_b16 v1, v90 offset:8064
	ds_write_b16_d16_hi v1, v90 offset:8208
	v_mfma_f32_32x32x16_bf16 v[32:47], v[248:251], v[116:119], v[32:47]
	v_cvt_pk_bf16_f32 v91, v142, v143
	ds_write_b16 v1, v91 offset:8352
	s_waitcnt lgkmcnt(7)
	ds_write_b16_d16_hi v1, v91 offset:8496
	v_mfma_f32_32x32x16_bf16 v[16:31], v[2:5], v[116:119], v[16:31]
	s_branch .LBB0_524
